# v46 + P0 cache conversion jobs: all five of a block's jobs requested up front (hand-written), then converted in order
# speedup vs baseline: 1.0022x; 1.0022x over previous
.Lcf_entry:
	s_sub_i32 s7, s89, s63
	v_lshl_add_u32 v26, s7, 9, v155
	v_add_u32_e32 v27, 0x20000, v26
	v_lshlrev_b32_e32 v28, 5, v26
	global_load_dwordx4 v[0:3], v28, s[20:21] nt
	global_load_dwordx4 v[4:7], v28, s[20:21] offset:16 nt
	v_lshlrev_b32_e32 v28, 5, v27
	global_load_dwordx4 v[8:11], v28, s[20:21] nt
	global_load_dwordx4 v[12:15], v28, s[20:21] offset:16 nt
	v_lshrrev_b32_e32 v28, 14, v26
	v_bfe_u32 v29, v26, 9, 5
	v_and_b32_e32 v24, 0x1ff, v26
	v_lshlrev_b32_e32 v28, 17, v28
	v_lshl_or_b32 v28, v29, 12, v28
	v_or_b32_e32 v28, v28, v24
	v_lshlrev_b32_e32 v28, 2, v28
	global_load_dword v30, v28, s[22:23]
	global_load_dword v31, v28, s[22:23] offset:2048
	v_add_u32_e32 v28, 0x1000, v28
	global_load_dword v32, v28, s[22:23]
	global_load_dword v33, v28, s[22:23] offset:2048
	v_add_u32_e32 v28, 0x1000, v28
	global_load_dword v34, v28, s[22:23]
	global_load_dword v35, v28, s[22:23] offset:2048
	v_add_u32_e32 v28, 0x1000, v28
	global_load_dword v36, v28, s[22:23]
	global_load_dword v37, v28, s[22:23] offset:2048
	v_lshrrev_b32_e32 v28, 14, v27
	v_bfe_u32 v29, v27, 9, 5
	v_and_b32_e32 v24, 0x1ff, v27
	v_lshlrev_b32_e32 v28, 17, v28
	v_lshl_or_b32 v28, v29, 12, v28
	v_or_b32_e32 v28, v28, v24
	v_lshlrev_b32_e32 v28, 2, v28
	global_load_dword v38, v28, s[22:23]
	global_load_dword v39, v28, s[22:23] offset:2048
	v_add_u32_e32 v28, 0x1000, v28
	global_load_dword v40, v28, s[22:23]
	global_load_dword v41, v28, s[22:23] offset:2048
	v_add_u32_e32 v28, 0x1000, v28
	global_load_dword v42, v28, s[22:23]
	global_load_dword v43, v28, s[22:23] offset:2048
	v_add_u32_e32 v28, 0x1000, v28
	global_load_dword v44, v28, s[22:23]
	global_load_dword v45, v28, s[22:23] offset:2048
	v_lshlrev_b32_e32 v28, 5, v26
	global_load_dwordx4 v[46:49], v28, s[2:3] nt
	global_load_dwordx4 v[50:53], v28, s[2:3] offset:16 nt
	v_lshlrev_b32_e32 v28, 3, v26
	v_bfe_u32 v29, v28, 17, 1
	v_lshrrev_b32_e32 v24, 18, v28
	v_and_b32_e32 v28, 0x1ffff, v28
	v_lshl_add_u32 v28, v29, 20, v28
	v_lshl_add_u32 v28, v24, 17, v28
	v_lshlrev_b32_e32 v28, 1, v28
	s_waitcnt vmcnt(20)
	v_cvt_pk_bf16_f32 v0, v0, v1
	v_cvt_pk_bf16_f32 v1, v2, v3
	v_cvt_pk_bf16_f32 v2, v4, v5
	v_cvt_pk_bf16_f32 v3, v6, v7
	global_store_dwordx4 v28, v[0:3], s[50:51]
	v_lshlrev_b32_e32 v28, 3, v27
	v_bfe_u32 v29, v28, 17, 1
	v_lshrrev_b32_e32 v24, 18, v28
	v_and_b32_e32 v28, 0x1ffff, v28
	v_lshl_add_u32 v28, v29, 20, v28
	v_lshl_add_u32 v28, v24, 17, v28
	v_lshlrev_b32_e32 v28, 1, v28
	s_waitcnt vmcnt(18)
	v_cvt_pk_bf16_f32 v8, v8, v9
	v_cvt_pk_bf16_f32 v9, v10, v11
	v_cvt_pk_bf16_f32 v10, v12, v13
	v_cvt_pk_bf16_f32 v11, v14, v15
	global_store_dwordx4 v28, v[8:11], s[50:51]
	v_bfe_u32 v29, v26, 14, 1
	v_lshrrev_b32_e32 v24, 15, v26
	v_and_b32_e32 v28, 0x1ff, v26
	v_lshlrev_b32_e32 v28, 8, v28
	v_lshl_add_u32 v28, v29, 20, v28
	v_lshl_add_u32 v28, v24, 17, v28
	v_bfe_u32 v29, v26, 9, 5
	v_lshl_add_u32 v28, v29, 3, v28
	v_lshlrev_b32_e32 v28, 1, v28
	s_waitcnt vmcnt(12)
	v_cvt_pk_bf16_f32 v30, v30, v31
	v_cvt_pk_bf16_f32 v31, v32, v33
	v_cvt_pk_bf16_f32 v32, v34, v35
	v_cvt_pk_bf16_f32 v33, v36, v37
	global_store_dwordx4 v28, v[30:33], s[52:53]
	v_bfe_u32 v29, v27, 14, 1
	v_lshrrev_b32_e32 v24, 15, v27
	v_and_b32_e32 v28, 0x1ff, v27
	v_lshlrev_b32_e32 v28, 8, v28
	v_lshl_add_u32 v28, v29, 20, v28
	v_lshl_add_u32 v28, v24, 17, v28
	v_bfe_u32 v29, v27, 9, 5
	v_lshl_add_u32 v28, v29, 3, v28
	v_lshlrev_b32_e32 v28, 1, v28
	s_waitcnt vmcnt(5)
	v_cvt_pk_bf16_f32 v38, v38, v39
	v_cvt_pk_bf16_f32 v39, v40, v41
	v_cvt_pk_bf16_f32 v40, v42, v43
	v_cvt_pk_bf16_f32 v41, v44, v45
	global_store_dwordx4 v28, v[38:41], s[52:53]
	v_lshlrev_b32_e32 v28, 3, v26
	v_bfe_u32 v29, v28, 16, 1
	v_lshrrev_b32_e32 v24, 17, v28
	v_and_b32_e32 v28, 0xffff, v28
	v_lshl_add_u32 v28, v29, 19, v28
	v_lshl_add_u32 v28, v24, 16, v28
	v_lshlrev_b32_e32 v28, 1, v28
	s_waitcnt vmcnt(4)
	v_cvt_pk_bf16_f32 v46, v46, v47
	v_cvt_pk_bf16_f32 v47, v48, v49
	v_cvt_pk_bf16_f32 v48, v50, v51
	v_cvt_pk_bf16_f32 v49, v52, v53
	global_store_dwordx4 v28, v[46:49], s[54:55]
	s_branch .LBB0_113

.LBB0_24:
	s_cmp_lt_i32 s89, s63
	s_cbranch_scc1 .Lcf_no
	s_cmpk_lg_u32 s61, 0x16e0
	s_cbranch_scc1 .Lcf_no
	s_sub_i32 s7, s89, s63
	s_cmpk_ge_u32 s7, 0x100
	s_cbranch_scc1 .Lcf_no
	s_load_dword s6, s[0:1], 0x4c8
	s_load_dwordx2 s[50:51], s[0:1], 0xf8
	s_waitcnt lgkmcnt(0)
	s_cmpk_lg_u32 s6, 0x100
	s_cbranch_scc1 .Lcf_no
	s_add_u32 s52, s50, 0xd14000
	s_addc_u32 s53, s51, 0
	s_add_u32 s54, s50, 0x1114000
	s_addc_u32 s55, s51, 0
	s_add_u32 s50, s50, 0x914000
	s_addc_u32 s51, s51, 0
	s_branch .Lcf_entry
